# rotate weight-transpose job start workgroups (max 8 tiles per WG), k8 GEMM loop fragment double buffering
# speedup vs baseline: 1.0074x; 1.0074x over previous
.LBB0_93:
	s_or_b64 exec, exec, s[2:3]
	v_readlane_b32 s0, v252, 21
	s_cmp_lg_u32 s0, 0
	v_readlane_b32 s1, v252, 22
	s_cbranch_scc1 .LBB0_152
	s_load_dwordx2 s[2:3], s[58:59], 0x20
	s_waitcnt vmcnt(6)
	v_mov_b32_e32 v4, v192
	s_add_i32 s12, s55, 128
	s_sub_i32 vcc_lo, s12, s62
	s_cmp_ge_u32 s12, s62
	s_cselect_b32 s12, vcc_lo, s12
	s_waitcnt lgkmcnt(0)
	s_add_u32 s0, s2, 0x1948000
	s_addc_u32 s1, s3, 0
	s_cmpk_gt_i32 s12, 0x27f
	s_movk_i32 s16, 0x6520
	s_cbranch_scc1 .LBB0_99
	v_and_b32_e32 v6, 63, v4
	v_lshlrev_b32_e32 v2, 1, v4
	v_ashrrev_i32_e32 v7, 5, v4
	s_waitcnt vmcnt(5)
	v_ashrrev_i32_e32 v9, 6, v4
	s_waitcnt vmcnt(1)
	v_add_u32_e32 v25, 0x100, v4
	v_add_u32_e32 v27, 0x200, v4
	s_waitcnt vmcnt(0)
	v_add_u32_e32 v29, 0x300, v4
	v_add_u32_e32 v31, 0x400, v4
	v_add_u32_e32 v33, 0x500, v4
	v_add_u32_e32 v35, 0x600, v4
	v_add_u32_e32 v37, 0x700, v4
	v_add_u32_e32 v17, 0x800, v4
	v_add_u32_e32 v18, 0x900, v4
	v_add_u32_e32 v19, 0xa00, v4
	v_add_u32_e32 v20, 0xb00, v4
	v_add_u32_e32 v21, 0xc00, v4
	v_add_u32_e32 v22, 0xd00, v4
	v_add_u32_e32 v23, 0xe00, v4
	v_add_u32_e32 v4, 0xf00, v4
	v_and_b32_e32 v5, 62, v2
	s_movk_i32 s6, 0x104
	v_ashrrev_i32_e32 v10, 6, v25
	v_ashrrev_i32_e32 v11, 6, v27
	v_ashrrev_i32_e32 v12, 6, v29
	v_ashrrev_i32_e32 v13, 6, v31
	v_ashrrev_i32_e32 v14, 6, v33
	v_ashrrev_i32_e32 v15, 6, v35
	v_ashrrev_i32_e32 v16, 6, v37
	v_ashrrev_i32_e32 v17, 6, v17
	v_ashrrev_i32_e32 v18, 6, v18
	v_ashrrev_i32_e32 v19, 6, v19
	v_ashrrev_i32_e32 v20, 6, v20
	v_ashrrev_i32_e32 v21, 6, v21
	v_ashrrev_i32_e32 v22, 6, v22
	v_ashrrev_i32_e32 v23, 6, v23
	v_ashrrev_i32_e32 v24, 6, v4
	v_ashrrev_i32_e32 v25, 5, v25
	v_ashrrev_i32_e32 v27, 5, v27
	v_ashrrev_i32_e32 v29, 5, v29
	v_ashrrev_i32_e32 v31, 5, v31
	v_ashrrev_i32_e32 v33, 5, v33
	v_ashrrev_i32_e32 v35, 5, v35
	v_ashrrev_i32_e32 v37, 5, v37
	v_lshlrev_b32_e32 v176, 2, v6
	v_lshlrev_b32_e32 v2, 1, v5
	v_mov_b32_e32 v3, v177
	v_lshlrev_b32_e32 v8, 2, v7
	v_mul_lo_u32 v39, v9, s6
	v_mul_lo_u32 v40, v10, s6
	v_mul_lo_u32 v41, v11, s6
	v_mul_lo_u32 v42, v12, s6
	v_mul_lo_u32 v43, v13, s6
	v_mul_lo_u32 v44, v14, s6
	v_mul_lo_u32 v45, v15, s6
	v_mul_lo_u32 v46, v16, s6
	v_mul_lo_u32 v47, v17, s6
	v_mul_lo_u32 v48, v18, s6
	v_mul_lo_u32 v49, v19, s6
	v_mul_lo_u32 v50, v20, s6
	v_mul_lo_u32 v51, v21, s6
	v_mul_lo_u32 v52, v22, s6
	v_mul_lo_u32 v53, v23, s6
	v_mul_lo_u32 v4, v24, s6
	v_lshlrev_b32_e32 v26, 2, v25
	v_lshlrev_b32_e32 v28, 2, v27
	v_lshlrev_b32_e32 v30, 2, v29
	v_lshlrev_b32_e32 v32, 2, v31
	v_lshlrev_b32_e32 v34, 2, v33
	v_lshlrev_b32_e32 v36, 2, v35
	v_lshlrev_b32_e32 v38, 2, v37
	v_lshl_add_u64 v[0:1], s[0:1], 0, v[176:177]
	v_lshl_add_u64 v[2:3], s[4:5], 0, v[2:3]
	v_mad_u32_u24 v8, v5, s6, v8
	v_mad_u32_u24 v26, v5, s6, v26
	v_mad_u32_u24 v28, v5, s6, v28
	v_mad_u32_u24 v30, v5, s6, v30
	v_mad_u32_u24 v32, v5, s6, v32
	v_mad_u32_u24 v34, v5, s6, v34
	v_mad_u32_u24 v36, v5, s6, v36
	v_mad_u32_u24 v38, v5, s6, v38
	v_add_u32_e32 v39, v176, v39
	v_add_u32_e32 v40, v176, v40
	v_add_u32_e32 v41, v176, v41
	v_add_u32_e32 v42, v176, v42
	v_add_u32_e32 v43, v176, v43
	v_add_u32_e32 v44, v176, v44
	v_add_u32_e32 v45, v176, v45
	v_add_u32_e32 v46, v176, v46
	v_add_u32_e32 v47, v176, v47
	v_add_u32_e32 v48, v176, v48
	v_add_u32_e32 v49, v176, v49
	v_add_u32_e32 v50, v176, v50
	v_add_u32_e32 v51, v176, v51
	v_add_u32_e32 v52, v176, v52
	v_add_u32_e32 v53, v176, v53
	v_add_u32_e32 v54, v176, v4
	s_branch .LBB0_97

.LBB0_99:
	v_mov_b32_e32 v4, v192
	s_add_i32 s12, s55, 256
	s_sub_i32 vcc_lo, s12, s62
	s_cmp_ge_u32 s12, s62
	s_cselect_b32 s12, vcc_lo, s12
	s_cmpk_gt_i32 s12, 0xdf
	s_cbranch_scc1 .LBB0_104
	v_and_b32_e32 v6, 63, v4
	v_lshlrev_b32_e32 v2, 1, v4
	v_lshlrev_b32_e32 v176, 2, v6
	v_and_b32_e32 v5, 62, v2
	v_lshl_add_u64 v[0:1], s[2:3], 0, v[176:177]
	s_mov_b64 s[6:7], 0x194b800
	v_lshlrev_b32_e32 v2, 1, v5
	v_mov_b32_e32 v3, v177
	v_lshl_add_u64 v[0:1], v[0:1], 0, s[6:7]
	v_lshl_add_u64 v[2:3], s[4:5], 0, v[2:3]
	s_mov_b64 s[6:7], 0x900000
	v_ashrrev_i32_e32 v7, 5, v4
	s_waitcnt vmcnt(5)
	v_ashrrev_i32_e32 v9, 6, v4
	s_waitcnt vmcnt(1)
	v_add_u32_e32 v25, 0x100, v4
	v_add_u32_e32 v27, 0x200, v4
	s_waitcnt vmcnt(0)
	v_add_u32_e32 v29, 0x300, v4
	v_add_u32_e32 v31, 0x400, v4
	v_add_u32_e32 v33, 0x500, v4
	v_add_u32_e32 v35, 0x600, v4
	v_add_u32_e32 v37, 0x700, v4
	v_add_u32_e32 v17, 0x800, v4
	v_add_u32_e32 v18, 0x900, v4
	v_add_u32_e32 v19, 0xa00, v4
	v_add_u32_e32 v20, 0xb00, v4
	v_add_u32_e32 v21, 0xc00, v4
	v_add_u32_e32 v22, 0xd00, v4
	v_add_u32_e32 v23, 0xe00, v4
	v_add_u32_e32 v4, 0xf00, v4
	v_lshl_add_u64 v[2:3], v[2:3], 0, s[6:7]
	s_movk_i32 s6, 0x104
	v_ashrrev_i32_e32 v10, 6, v25
	v_ashrrev_i32_e32 v11, 6, v27
	v_ashrrev_i32_e32 v12, 6, v29
	v_ashrrev_i32_e32 v13, 6, v31
	v_ashrrev_i32_e32 v14, 6, v33
	v_ashrrev_i32_e32 v15, 6, v35
	v_ashrrev_i32_e32 v16, 6, v37
	v_ashrrev_i32_e32 v17, 6, v17
	v_ashrrev_i32_e32 v18, 6, v18
	v_ashrrev_i32_e32 v19, 6, v19
	v_ashrrev_i32_e32 v20, 6, v20
	v_ashrrev_i32_e32 v21, 6, v21
	v_ashrrev_i32_e32 v22, 6, v22
	v_ashrrev_i32_e32 v23, 6, v23
	v_ashrrev_i32_e32 v24, 6, v4
	v_ashrrev_i32_e32 v25, 5, v25
	v_ashrrev_i32_e32 v27, 5, v27
	v_ashrrev_i32_e32 v29, 5, v29
	v_ashrrev_i32_e32 v31, 5, v31
	v_ashrrev_i32_e32 v33, 5, v33
	v_ashrrev_i32_e32 v35, 5, v35
	v_ashrrev_i32_e32 v37, 5, v37
	v_lshlrev_b32_e32 v8, 2, v7
	v_mul_lo_u32 v39, v9, s6
	v_mul_lo_u32 v40, v10, s6
	v_mul_lo_u32 v41, v11, s6
	v_mul_lo_u32 v42, v12, s6
	v_mul_lo_u32 v43, v13, s6
	v_mul_lo_u32 v44, v14, s6
	v_mul_lo_u32 v45, v15, s6
	v_mul_lo_u32 v46, v16, s6
	v_mul_lo_u32 v47, v17, s6
	v_mul_lo_u32 v48, v18, s6
	v_mul_lo_u32 v49, v19, s6
	v_mul_lo_u32 v50, v20, s6
	v_mul_lo_u32 v51, v21, s6
	v_mul_lo_u32 v52, v22, s6
	v_mul_lo_u32 v53, v23, s6
	v_mul_lo_u32 v4, v24, s6
	v_lshlrev_b32_e32 v26, 2, v25
	v_lshlrev_b32_e32 v28, 2, v27
	v_lshlrev_b32_e32 v30, 2, v29
	v_lshlrev_b32_e32 v32, 2, v31
	v_lshlrev_b32_e32 v34, 2, v33
	v_lshlrev_b32_e32 v36, 2, v35
	v_lshlrev_b32_e32 v38, 2, v37
	v_mad_u32_u24 v8, v5, s6, v8
	v_mad_u32_u24 v26, v5, s6, v26
	v_mad_u32_u24 v28, v5, s6, v28
	v_mad_u32_u24 v30, v5, s6, v30
	v_mad_u32_u24 v32, v5, s6, v32
	v_mad_u32_u24 v34, v5, s6, v34
	v_mad_u32_u24 v36, v5, s6, v36
	v_mad_u32_u24 v38, v5, s6, v38
	v_add_u32_e32 v39, v176, v39
	v_add_u32_e32 v40, v176, v40
	v_add_u32_e32 v41, v176, v41
	v_add_u32_e32 v42, v176, v42
	v_add_u32_e32 v43, v176, v43
	v_add_u32_e32 v44, v176, v44
	v_add_u32_e32 v45, v176, v45
	v_add_u32_e32 v46, v176, v46
	v_add_u32_e32 v47, v176, v47
	v_add_u32_e32 v48, v176, v48
	v_add_u32_e32 v49, v176, v49
	v_add_u32_e32 v50, v176, v50
	v_add_u32_e32 v51, v176, v51
	v_add_u32_e32 v52, v176, v52
	v_add_u32_e32 v53, v176, v53
	v_add_u32_e32 v54, v176, v4
	s_branch .LBB0_102

.LBB0_109:
	s_waitcnt vmcnt(2)
	v_mov_b32_e32 v22, v192
	s_add_i32 s10, s55, 32
	s_sub_i32 vcc_lo, s10, s62
	s_cmp_ge_u32 s10, s62
	s_cselect_b32 s10, vcc_lo, s10
	s_cmpk_gt_i32 s10, 0x13f
	s_cbranch_scc1 .LBB0_114
	s_load_dwordx2 s[2:3], s[58:59], 0x78
	v_and_b32_e32 v4, 63, v22
	v_lshlrev_b32_e32 v0, 1, v22
	v_lshlrev_b32_e32 v176, 2, v4
	v_and_b32_e32 v36, 62, v0
	s_waitcnt lgkmcnt(0)
	v_lshl_add_u64 v[0:1], s[2:3], 0, v[176:177]
	s_mov_b64 s[2:3], 0x500000
	v_lshlrev_b32_e32 v2, 1, v36
	v_mov_b32_e32 v3, v177
	v_lshl_add_u64 v[0:1], v[0:1], 0, s[2:3]
	v_lshl_add_u64 v[2:3], s[4:5], 0, v[2:3]
	s_mov_b64 s[2:3], 0x12c0000
	v_ashrrev_i32_e32 v5, 5, v22
	v_ashrrev_i32_e32 v7, 6, v22
	v_add_u32_e32 v23, 0x100, v22
	s_waitcnt vmcnt(1)
	v_add_u32_e32 v25, 0x200, v22
	v_add_u32_e32 v27, 0x300, v22
	s_waitcnt vmcnt(0)
	v_add_u32_e32 v29, 0x400, v22
	v_add_u32_e32 v31, 0x500, v22
	v_add_u32_e32 v33, 0x600, v22
	v_add_u32_e32 v35, 0x700, v22
	v_add_u32_e32 v15, 0x800, v22
	v_add_u32_e32 v16, 0x900, v22
	v_add_u32_e32 v17, 0xa00, v22
	v_add_u32_e32 v18, 0xb00, v22
	v_add_u32_e32 v19, 0xc00, v22
	v_add_u32_e32 v20, 0xd00, v22
	v_add_u32_e32 v21, 0xe00, v22
	v_add_u32_e32 v22, 0xf00, v22
	v_lshl_add_u64 v[2:3], v[2:3], 0, s[2:3]
	s_movk_i32 s2, 0x104
	v_ashrrev_i32_e32 v8, 6, v23
	v_ashrrev_i32_e32 v9, 6, v25
	v_ashrrev_i32_e32 v10, 6, v27
	v_ashrrev_i32_e32 v11, 6, v29
	v_ashrrev_i32_e32 v12, 6, v31
	v_ashrrev_i32_e32 v13, 6, v33
	v_ashrrev_i32_e32 v14, 6, v35
	v_ashrrev_i32_e32 v15, 6, v15
	v_ashrrev_i32_e32 v16, 6, v16
	v_ashrrev_i32_e32 v17, 6, v17
	v_ashrrev_i32_e32 v18, 6, v18
	v_ashrrev_i32_e32 v19, 6, v19
	v_ashrrev_i32_e32 v20, 6, v20
	v_ashrrev_i32_e32 v21, 6, v21
	v_ashrrev_i32_e32 v22, 6, v22
	v_ashrrev_i32_e32 v23, 5, v23
	v_ashrrev_i32_e32 v25, 5, v25
	v_ashrrev_i32_e32 v27, 5, v27
	v_ashrrev_i32_e32 v29, 5, v29
	v_ashrrev_i32_e32 v31, 5, v31
	v_ashrrev_i32_e32 v33, 5, v33
	v_ashrrev_i32_e32 v35, 5, v35
	v_lshlrev_b32_e32 v6, 2, v5
	v_mul_lo_u32 v37, v7, s2
	v_mul_lo_u32 v38, v8, s2
	v_mul_lo_u32 v39, v9, s2
	v_mul_lo_u32 v40, v10, s2
	v_mul_lo_u32 v41, v11, s2
	v_mul_lo_u32 v42, v12, s2
	v_mul_lo_u32 v43, v13, s2
	v_mul_lo_u32 v44, v14, s2
	v_mul_lo_u32 v45, v15, s2
	v_mul_lo_u32 v46, v16, s2
	v_mul_lo_u32 v47, v17, s2
	v_mul_lo_u32 v48, v18, s2
	v_mul_lo_u32 v49, v19, s2
	v_mul_lo_u32 v50, v20, s2
	v_mul_lo_u32 v51, v21, s2
	v_mul_lo_u32 v52, v22, s2
	v_lshlrev_b32_e32 v24, 2, v23
	v_lshlrev_b32_e32 v26, 2, v25
	v_lshlrev_b32_e32 v28, 2, v27
	v_lshlrev_b32_e32 v30, 2, v29
	v_lshlrev_b32_e32 v32, 2, v31
	v_lshlrev_b32_e32 v34, 2, v33
	v_lshlrev_b32_e32 v53, 2, v35
	v_mad_u32_u24 v6, v36, s2, v6
	v_mad_u32_u24 v24, v36, s2, v24
	v_mad_u32_u24 v26, v36, s2, v26
	v_mad_u32_u24 v28, v36, s2, v28
	v_mad_u32_u24 v30, v36, s2, v30
	v_mad_u32_u24 v32, v36, s2, v32
	v_mad_u32_u24 v34, v36, s2, v34
	v_mad_u32_u24 v36, v36, s2, v53
	v_add_u32_e32 v37, v176, v37
	v_add_u32_e32 v38, v176, v38
	v_add_u32_e32 v39, v176, v39
	v_add_u32_e32 v40, v176, v40
	v_add_u32_e32 v41, v176, v41
	v_add_u32_e32 v42, v176, v42
	v_add_u32_e32 v43, v176, v43
	v_add_u32_e32 v44, v176, v44
	v_add_u32_e32 v45, v176, v45
	v_add_u32_e32 v46, v176, v46
	v_add_u32_e32 v47, v176, v47
	v_add_u32_e32 v48, v176, v48
	v_add_u32_e32 v49, v176, v49
	v_add_u32_e32 v50, v176, v50
	v_add_u32_e32 v51, v176, v51
	v_add_u32_e32 v52, v176, v52
	s_branch .LBB0_112

.LBB0_131:
	s_lshl_b32 s56, s16, 14
	v_mov_b32_e32 v4, v192
	s_lshl_b32 s17, s16, 3
	s_sub_i32 s17, s55, s17
	s_cmp_ge_u32 s62, 0x200
	s_cselect_b32 vcc_lo, 0xfffffee0, 0
	s_add_i32 s17, s17, vcc_lo
	s_cmp_gt_u32 s17, 3
	s_cbranch_scc1 .LBB0_136
	s_lshl_b32 s2, s56, 1
	v_lshlrev_b32_e32 v2, 1, v4
	s_add_u32 s2, s10, s2
	v_and_b32_e32 v5, 62, v2
	s_addc_u32 s3, s11, 0
	s_lshl_b64 s[6:7], s[56:57], 2
	v_and_b32_e32 v6, 63, v4
	v_lshlrev_b32_e32 v2, 1, v5
	v_mov_b32_e32 v3, v177
	v_ashrrev_i32_e32 v7, 5, v4
	v_ashrrev_i32_e32 v9, 6, v4
	s_waitcnt vmcnt(1)
	v_add_u32_e32 v25, 0x100, v4
	v_add_u32_e32 v27, 0x200, v4
	s_waitcnt vmcnt(0)
	v_add_u32_e32 v29, 0x300, v4
	v_add_u32_e32 v31, 0x400, v4
	v_add_u32_e32 v33, 0x500, v4
	v_add_u32_e32 v35, 0x600, v4
	v_add_u32_e32 v37, 0x700, v4
	v_add_u32_e32 v17, 0x800, v4
	v_add_u32_e32 v18, 0x900, v4
	v_add_u32_e32 v19, 0xa00, v4
	v_add_u32_e32 v20, 0xb00, v4
	v_add_u32_e32 v21, 0xc00, v4
	v_add_u32_e32 v22, 0xd00, v4
	v_add_u32_e32 v23, 0xe00, v4
	v_add_u32_e32 v4, 0xf00, v4
	s_add_u32 s6, s12, s6
	v_lshl_add_u64 v[2:3], s[2:3], 0, v[2:3]
	s_movk_i32 s2, 0x104
	v_ashrrev_i32_e32 v10, 6, v25
	v_ashrrev_i32_e32 v11, 6, v27
	v_ashrrev_i32_e32 v12, 6, v29
	v_ashrrev_i32_e32 v13, 6, v31
	v_ashrrev_i32_e32 v14, 6, v33
	v_ashrrev_i32_e32 v15, 6, v35
	v_ashrrev_i32_e32 v16, 6, v37
	v_ashrrev_i32_e32 v17, 6, v17
	v_ashrrev_i32_e32 v18, 6, v18
	v_ashrrev_i32_e32 v19, 6, v19
	v_ashrrev_i32_e32 v20, 6, v20
	v_ashrrev_i32_e32 v21, 6, v21
	v_ashrrev_i32_e32 v22, 6, v22
	v_ashrrev_i32_e32 v23, 6, v23
	v_ashrrev_i32_e32 v24, 6, v4
	v_ashrrev_i32_e32 v25, 5, v25
	v_ashrrev_i32_e32 v27, 5, v27
	v_ashrrev_i32_e32 v29, 5, v29
	v_ashrrev_i32_e32 v31, 5, v31
	v_ashrrev_i32_e32 v33, 5, v33
	v_ashrrev_i32_e32 v35, 5, v35
	v_ashrrev_i32_e32 v37, 5, v37
	s_addc_u32 s7, s13, s7
	v_lshlrev_b32_e32 v176, 2, v6
	v_lshlrev_b32_e32 v8, 2, v7
	v_mul_lo_u32 v39, v9, s2
	v_mul_lo_u32 v40, v10, s2
	v_mul_lo_u32 v41, v11, s2
	v_mul_lo_u32 v42, v12, s2
	v_mul_lo_u32 v43, v13, s2
	v_mul_lo_u32 v44, v14, s2
	v_mul_lo_u32 v45, v15, s2
	v_mul_lo_u32 v46, v16, s2
	v_mul_lo_u32 v47, v17, s2
	v_mul_lo_u32 v48, v18, s2
	v_mul_lo_u32 v49, v19, s2
	v_mul_lo_u32 v50, v20, s2
	v_mul_lo_u32 v51, v21, s2
	v_mul_lo_u32 v52, v22, s2
	v_mul_lo_u32 v53, v23, s2
	v_mul_lo_u32 v4, v24, s2
	v_lshlrev_b32_e32 v26, 2, v25
	v_lshlrev_b32_e32 v28, 2, v27
	v_lshlrev_b32_e32 v30, 2, v29
	v_lshlrev_b32_e32 v32, 2, v31
	v_lshlrev_b32_e32 v34, 2, v33
	v_lshlrev_b32_e32 v36, 2, v35
	v_lshlrev_b32_e32 v38, 2, v37
	v_lshl_add_u64 v[0:1], s[6:7], 0, v[176:177]
	v_mad_u32_u24 v8, v5, s2, v8
	v_mad_u32_u24 v26, v5, s2, v26
	v_mad_u32_u24 v28, v5, s2, v28
	v_mad_u32_u24 v30, v5, s2, v30
	v_mad_u32_u24 v32, v5, s2, v32
	v_mad_u32_u24 v34, v5, s2, v34
	v_mad_u32_u24 v36, v5, s2, v36
	v_mad_u32_u24 v38, v5, s2, v38
	v_add_u32_e32 v39, v176, v39
	v_add_u32_e32 v40, v176, v40
	v_add_u32_e32 v41, v176, v41
	v_add_u32_e32 v42, v176, v42
	v_add_u32_e32 v43, v176, v43
	v_add_u32_e32 v44, v176, v44
	v_add_u32_e32 v45, v176, v45
	v_add_u32_e32 v46, v176, v46
	v_add_u32_e32 v47, v176, v47
	v_add_u32_e32 v48, v176, v48
	v_add_u32_e32 v49, v176, v49
	v_add_u32_e32 v50, v176, v50
	v_add_u32_e32 v51, v176, v51
	v_add_u32_e32 v52, v176, v52
	v_add_u32_e32 v53, v176, v53
	v_add_u32_e32 v54, v176, v4
	s_branch .LBB0_134

.LBB0_136:
	v_mov_b32_e32 v4, v192
	s_lshl_b32 s17, s16, 3
	s_sub_i32 s17, s55, s17
	s_cmp_ge_u32 s62, 0x200
	s_cselect_b32 vcc_lo, 0xfffffee0, 0
	s_add_i32 s17, s17, vcc_lo
	s_add_i32 s17, s17, -4
	s_cmp_gt_u32 s17, 3
	s_cbranch_scc1 .LBB0_130
	s_load_dwordx2 s[2:3], s[58:59], 0x48
	s_lshl_b32 s6, s56, 1
	s_add_u32 s6, s14, s6
	s_addc_u32 s7, s15, 0
	s_lshl_b64 s[8:9], s[56:57], 2
	s_waitcnt lgkmcnt(0)
	s_add_u32 s2, s2, s8
	v_and_b32_e32 v6, 63, v4
	s_addc_u32 s3, s3, s9
	v_lshlrev_b32_e32 v176, 2, v6
	v_lshl_add_u64 v[0:1], s[2:3], 0, v[176:177]
	s_mov_b64 s[2:3], 0xa0000
	v_lshlrev_b32_e32 v2, 1, v4
	v_ashrrev_i32_e32 v7, 5, v4
	v_ashrrev_i32_e32 v9, 6, v4
	s_waitcnt vmcnt(1)
	v_add_u32_e32 v25, 0x100, v4
	v_add_u32_e32 v27, 0x200, v4
	s_waitcnt vmcnt(0)
	v_add_u32_e32 v29, 0x300, v4
	v_add_u32_e32 v31, 0x400, v4
	v_add_u32_e32 v33, 0x500, v4
	v_add_u32_e32 v35, 0x600, v4
	v_add_u32_e32 v37, 0x700, v4
	v_add_u32_e32 v17, 0x800, v4
	v_add_u32_e32 v18, 0x900, v4
	v_add_u32_e32 v19, 0xa00, v4
	v_add_u32_e32 v20, 0xb00, v4
	v_add_u32_e32 v21, 0xc00, v4
	v_add_u32_e32 v22, 0xd00, v4
	v_add_u32_e32 v23, 0xe00, v4
	v_add_u32_e32 v4, 0xf00, v4
	v_lshl_add_u64 v[0:1], v[0:1], 0, s[2:3]
	v_and_b32_e32 v5, 62, v2
	s_movk_i32 s2, 0x104
	v_ashrrev_i32_e32 v10, 6, v25
	v_ashrrev_i32_e32 v11, 6, v27
	v_ashrrev_i32_e32 v12, 6, v29
	v_ashrrev_i32_e32 v13, 6, v31
	v_ashrrev_i32_e32 v14, 6, v33
	v_ashrrev_i32_e32 v15, 6, v35
	v_ashrrev_i32_e32 v16, 6, v37
	v_ashrrev_i32_e32 v17, 6, v17
	v_ashrrev_i32_e32 v18, 6, v18
	v_ashrrev_i32_e32 v19, 6, v19
	v_ashrrev_i32_e32 v20, 6, v20
	v_ashrrev_i32_e32 v21, 6, v21
	v_ashrrev_i32_e32 v22, 6, v22
	v_ashrrev_i32_e32 v23, 6, v23
	v_ashrrev_i32_e32 v24, 6, v4
	v_ashrrev_i32_e32 v25, 5, v25
	v_ashrrev_i32_e32 v27, 5, v27
	v_ashrrev_i32_e32 v29, 5, v29
	v_ashrrev_i32_e32 v31, 5, v31
	v_ashrrev_i32_e32 v33, 5, v33
	v_ashrrev_i32_e32 v35, 5, v35
	v_ashrrev_i32_e32 v37, 5, v37
	v_lshlrev_b32_e32 v2, 1, v5
	v_mov_b32_e32 v3, v177
	v_lshlrev_b32_e32 v8, 2, v7
	v_mul_lo_u32 v39, v9, s2
	v_mul_lo_u32 v40, v10, s2
	v_mul_lo_u32 v41, v11, s2
	v_mul_lo_u32 v42, v12, s2
	v_mul_lo_u32 v43, v13, s2
	v_mul_lo_u32 v44, v14, s2
	v_mul_lo_u32 v45, v15, s2
	v_mul_lo_u32 v46, v16, s2
	v_mul_lo_u32 v47, v17, s2
	v_mul_lo_u32 v48, v18, s2
	v_mul_lo_u32 v49, v19, s2
	v_mul_lo_u32 v50, v20, s2
	v_mul_lo_u32 v51, v21, s2
	v_mul_lo_u32 v52, v22, s2
	v_mul_lo_u32 v53, v23, s2
	v_mul_lo_u32 v4, v24, s2
	v_lshlrev_b32_e32 v26, 2, v25
	v_lshlrev_b32_e32 v28, 2, v27
	v_lshlrev_b32_e32 v30, 2, v29
	v_lshlrev_b32_e32 v32, 2, v31
	v_lshlrev_b32_e32 v34, 2, v33
	v_lshlrev_b32_e32 v36, 2, v35
	v_lshlrev_b32_e32 v38, 2, v37
	v_lshl_add_u64 v[2:3], s[6:7], 0, v[2:3]
	v_mad_u32_u24 v8, v5, s2, v8
	v_mad_u32_u24 v26, v5, s2, v26
	v_mad_u32_u24 v28, v5, s2, v28
	v_mad_u32_u24 v30, v5, s2, v30
	v_mad_u32_u24 v32, v5, s2, v32
	v_mad_u32_u24 v34, v5, s2, v34
	v_mad_u32_u24 v36, v5, s2, v36
	v_mad_u32_u24 v38, v5, s2, v38
	v_add_u32_e32 v39, v176, v39
	v_add_u32_e32 v40, v176, v40
	v_add_u32_e32 v41, v176, v41
	v_add_u32_e32 v42, v176, v42
	v_add_u32_e32 v43, v176, v43
	v_add_u32_e32 v44, v176, v44
	v_add_u32_e32 v45, v176, v45
	v_add_u32_e32 v46, v176, v46
	v_add_u32_e32 v47, v176, v47
	v_add_u32_e32 v48, v176, v48
	v_add_u32_e32 v49, v176, v49
	v_add_u32_e32 v50, v176, v50
	v_add_u32_e32 v51, v176, v51
	v_add_u32_e32 v52, v176, v52
	v_add_u32_e32 v53, v176, v53
	v_add_u32_e32 v54, v176, v4
	s_branch .LBB0_139

.Lxk_206:
	ds_read_b128 v[220:223], v136
	ds_read_b128 v[224:227], v136 offset:2048
	ds_read_b128 v[228:231], v136 offset:4096
	ds_read_b128 v[232:235], v136 offset:6144
	ds_read_b128 v[236:239], v137 offset:16384
	ds_read_b128 v[240:243], v137 offset:18432
	ds_read_b128 v[244:247], v137 offset:20480
	ds_read_b128 v[248:251], v137 offset:22528
	s_waitcnt lgkmcnt(8)
	v_mfma_f32_16x16x32_bf16 v[124:127], v[154:157], v[138:141], v[124:127]
	s_add_i32 s5, s5, 2
	v_mfma_f32_16x16x32_bf16 v[120:123], v[158:161], v[138:141], v[120:123]
	s_min_u32 s7, s5, 12
	v_mfma_f32_16x16x32_bf16 v[116:119], v[162:165], v[138:141], v[116:119]
	s_lshl_b32 s56, s7, 7
	v_mfma_f32_16x16x32_bf16 v[112:115], v[166:169], v[138:141], v[112:115]
	s_min_u32 s7, s5, 11
	v_mfma_f32_16x16x32_bf16 v[108:111], v[154:157], v[142:145], v[108:111]
	s_waitcnt vmcnt(15)
	v_mfma_f32_16x16x32_bf16 v[104:107], v[158:161], v[142:145], v[104:107]
	ds_write_b128 v133, v[0:3] offset:32768
	v_mfma_f32_16x16x32_bf16 v[100:103], v[162:165], v[142:145], v[100:103]
	s_waitcnt vmcnt(11)
	v_mfma_f32_16x16x32_bf16 v[96:99], v[166:169], v[142:145], v[96:99]
	ds_write_b128 v133, v[8:11] offset:49152
	v_mfma_f32_16x16x32_bf16 v[92:95], v[154:157], v[146:149], v[92:95]
	ds_write_b128 v133, v[4:7] offset:36864
	v_mfma_f32_16x16x32_bf16 v[88:91], v[158:161], v[146:149], v[88:91]
	s_waitcnt vmcnt(10)
	v_mfma_f32_16x16x32_bf16 v[84:87], v[162:165], v[146:149], v[84:87]
	ds_write_b128 v133, v[12:15] offset:53248
	v_mfma_f32_16x16x32_bf16 v[80:83], v[166:169], v[146:149], v[80:83]
	ds_write_b128 v133, v[16:19] offset:40960
	v_mfma_f32_16x16x32_bf16 v[76:79], v[154:157], v[150:153], v[76:79]
	s_waitcnt vmcnt(9)
	v_mfma_f32_16x16x32_bf16 v[72:75], v[158:161], v[150:153], v[72:75]
	ds_write_b128 v133, v[20:23] offset:57344
	v_mfma_f32_16x16x32_bf16 v[68:71], v[162:165], v[150:153], v[68:71]
	ds_write_b128 v133, v[24:27] offset:45056
	v_mfma_f32_16x16x32_bf16 v[64:67], v[166:169], v[150:153], v[64:67]
	s_waitcnt vmcnt(8)
	ds_write_b128 v133, v[28:31] offset:61440
	s_waitcnt lgkmcnt(0)
	s_barrier
	ds_read_b128 v[138:141], v134 offset:32768
	ds_read_b128 v[142:145], v134 offset:34816
	ds_read_b128 v[146:149], v134 offset:36864
	ds_read_b128 v[150:153], v134 offset:38912
	ds_read_b128 v[154:157], v135 offset:49152
	ds_read_b128 v[158:161], v135 offset:51200
	ds_read_b128 v[162:165], v135 offset:53248
	ds_read_b128 v[166:169], v135 offset:55296
	v_mfma_f32_16x16x32_bf16 v[124:127], v[236:239], v[220:223], v[124:127]
	v_lshl_add_u64 v[24:25], v[128:129], 0, s[56:57]
	v_mfma_f32_16x16x32_bf16 v[120:123], v[240:243], v[220:223], v[120:123]
	v_add_co_u32_e32 v4, vcc, s65, v24
	v_lshl_add_u64 v[28:29], v[130:131], 0, s[56:57]
	v_mfma_f32_16x16x32_bf16 v[116:119], v[244:247], v[220:223], v[116:119]
	s_nop 0
	v_mfma_f32_16x16x32_bf16 v[112:115], v[248:251], v[220:223], v[112:115]
	v_addc_co_u32_e32 v5, vcc, 0, v25, vcc
	v_add_co_u32_e32 v12, vcc, s65, v28
	v_mfma_f32_16x16x32_bf16 v[108:111], v[236:239], v[224:227], v[108:111]
	global_load_dwordx4 v[0:3], v[24:25], off offset:384
	v_mfma_f32_16x16x32_bf16 v[104:107], v[240:243], v[224:227], v[104:107]
	global_load_dwordx4 v[8:11], v[28:29], off offset:384
	v_addc_co_u32_e32 v13, vcc, 0, v29, vcc
	v_mfma_f32_16x16x32_bf16 v[100:103], v[244:247], v[224:227], v[100:103]
	v_add_co_u32_e32 v16, vcc, s46, v24
	v_mfma_f32_16x16x32_bf16 v[96:99], v[248:251], v[224:227], v[96:99]
	s_nop 0
	v_addc_co_u32_e32 v17, vcc, 0, v25, vcc
	v_add_co_u32_e32 v20, vcc, s46, v28
	v_mfma_f32_16x16x32_bf16 v[92:95], v[236:239], v[228:231], v[92:95]
	s_nop 0
	v_addc_co_u32_e32 v21, vcc, 0, v29, vcc
	v_add_co_u32_e32 v24, vcc, s47, v24
	v_mfma_f32_16x16x32_bf16 v[88:91], v[240:243], v[228:231], v[88:91]
	s_nop 0
	v_addc_co_u32_e32 v25, vcc, 0, v25, vcc
	v_mfma_f32_16x16x32_bf16 v[84:87], v[244:247], v[228:231], v[84:87]
	v_add_co_u32_e32 v28, vcc, s47, v28
	s_nop 1
	v_addc_co_u32_e32 v29, vcc, 0, v29, vcc
	v_mfma_f32_16x16x32_bf16 v[80:83], v[248:251], v[228:231], v[80:83]
	global_load_dwordx4 v[4:7], v[4:5], off offset:384
	v_mfma_f32_16x16x32_bf16 v[76:79], v[236:239], v[232:235], v[76:79]
	global_load_dwordx4 v[12:15], v[12:13], off offset:384
	s_lshl_b32 s56, s7, 7
	v_mfma_f32_16x16x32_bf16 v[72:75], v[240:243], v[232:235], v[72:75]
	global_load_dwordx4 v[16:19], v[16:17], off offset:384
	v_mfma_f32_16x16x32_bf16 v[68:71], v[244:247], v[232:235], v[68:71]
	global_load_dwordx4 v[20:23], v[20:21], off offset:384
	s_cmp_lt_u32 s5, 14
	v_mfma_f32_16x16x32_bf16 v[64:67], v[248:251], v[232:235], v[64:67]
	global_load_dwordx4 v[24:27], v[24:25], off offset:384
	global_load_dwordx4 v[28:31], v[28:29], off offset:384
	ds_read_b128 v[220:223], v136 offset:32768
	ds_read_b128 v[224:227], v136 offset:34816
	ds_read_b128 v[228:231], v136 offset:36864
	ds_read_b128 v[232:235], v136 offset:38912
	ds_read_b128 v[236:239], v137 offset:49152
	ds_read_b128 v[240:243], v137 offset:51200
	ds_read_b128 v[244:247], v137 offset:53248
	ds_read_b128 v[248:251], v137 offset:55296
	s_waitcnt lgkmcnt(8)
	v_mfma_f32_16x16x32_bf16 v[124:127], v[154:157], v[138:141], v[124:127]
	s_waitcnt vmcnt(15)
	v_mfma_f32_16x16x32_bf16 v[120:123], v[158:161], v[138:141], v[120:123]
	ds_write_b128 v133, v[32:35]
	v_mfma_f32_16x16x32_bf16 v[116:119], v[162:165], v[138:141], v[116:119]
	s_waitcnt vmcnt(14)
	v_mfma_f32_16x16x32_bf16 v[112:115], v[166:169], v[138:141], v[112:115]
	ds_write_b128 v133, v[36:39] offset:16384
	v_mfma_f32_16x16x32_bf16 v[108:111], v[154:157], v[142:145], v[108:111]
	s_waitcnt vmcnt(13)
	v_mfma_f32_16x16x32_bf16 v[104:107], v[158:161], v[142:145], v[104:107]
	ds_write_b128 v133, v[40:43] offset:4096
	v_mfma_f32_16x16x32_bf16 v[100:103], v[162:165], v[142:145], v[100:103]
	s_waitcnt vmcnt(12)
	v_mfma_f32_16x16x32_bf16 v[96:99], v[166:169], v[142:145], v[96:99]
	ds_write_b128 v133, v[44:47] offset:20480
	v_mfma_f32_16x16x32_bf16 v[92:95], v[154:157], v[146:149], v[92:95]
	s_waitcnt vmcnt(11)
	v_mfma_f32_16x16x32_bf16 v[88:91], v[158:161], v[146:149], v[88:91]
	ds_write_b128 v133, v[48:51] offset:8192
	v_mfma_f32_16x16x32_bf16 v[84:87], v[162:165], v[146:149], v[84:87]
	s_waitcnt vmcnt(10)
	v_mfma_f32_16x16x32_bf16 v[80:83], v[166:169], v[146:149], v[80:83]
	ds_write_b128 v133, v[52:55] offset:24576
	v_mfma_f32_16x16x32_bf16 v[76:79], v[154:157], v[150:153], v[76:79]
	s_waitcnt vmcnt(9)
	v_mfma_f32_16x16x32_bf16 v[72:75], v[158:161], v[150:153], v[72:75]
	ds_write_b128 v133, v[56:59] offset:12288
	v_mfma_f32_16x16x32_bf16 v[68:71], v[162:165], v[150:153], v[68:71]
	s_waitcnt vmcnt(8)
	v_mfma_f32_16x16x32_bf16 v[64:67], v[166:169], v[150:153], v[64:67]
	ds_write_b128 v133, v[60:63] offset:28672
	s_waitcnt lgkmcnt(0)
	s_barrier
	ds_read_b128 v[138:141], v134
	ds_read_b128 v[142:145], v134 offset:2048
	ds_read_b128 v[146:149], v134 offset:4096
	ds_read_b128 v[150:153], v134 offset:6144
	ds_read_b128 v[154:157], v135 offset:16384
	ds_read_b128 v[158:161], v135 offset:18432
	ds_read_b128 v[162:165], v135 offset:20480
	ds_read_b128 v[166:169], v135 offset:22528
	v_mfma_f32_16x16x32_bf16 v[124:127], v[236:239], v[220:223], v[124:127]
	v_lshl_add_u64 v[56:57], v[128:129], 0, s[56:57]
	v_mfma_f32_16x16x32_bf16 v[120:123], v[240:243], v[220:223], v[120:123]
	v_add_co_u32_e32 v40, vcc, s65, v56
	v_lshl_add_u64 v[60:61], v[130:131], 0, s[56:57]
	v_mfma_f32_16x16x32_bf16 v[116:119], v[244:247], v[220:223], v[116:119]
	s_nop 0
	v_addc_co_u32_e32 v41, vcc, 0, v57, vcc
	v_mfma_f32_16x16x32_bf16 v[112:115], v[248:251], v[220:223], v[112:115]
	v_add_co_u32_e32 v44, vcc, s65, v60
	v_mfma_f32_16x16x32_bf16 v[108:111], v[236:239], v[224:227], v[108:111]
	global_load_dwordx4 v[32:35], v[56:57], off offset:512
	global_load_dwordx4 v[36:39], v[60:61], off offset:512
	v_mfma_f32_16x16x32_bf16 v[104:107], v[240:243], v[224:227], v[104:107]
	v_addc_co_u32_e32 v45, vcc, 0, v61, vcc
	v_add_co_u32_e32 v48, vcc, s46, v56
	v_mfma_f32_16x16x32_bf16 v[100:103], v[244:247], v[224:227], v[100:103]
	global_load_dwordx4 v[40:43], v[40:41], off offset:512
	v_mfma_f32_16x16x32_bf16 v[96:99], v[248:251], v[224:227], v[96:99]
	s_nop 0
	v_addc_co_u32_e32 v49, vcc, 0, v57, vcc
	v_mfma_f32_16x16x32_bf16 v[92:95], v[236:239], v[228:231], v[92:95]
	v_add_co_u32_e32 v52, vcc, s46, v60
	global_load_dwordx4 v[44:47], v[44:45], off offset:512
	v_mfma_f32_16x16x32_bf16 v[88:91], v[240:243], v[228:231], v[88:91]
	s_nop 0
	v_mfma_f32_16x16x32_bf16 v[84:87], v[244:247], v[228:231], v[84:87]
	v_addc_co_u32_e32 v53, vcc, 0, v61, vcc
	v_add_co_u32_e32 v56, vcc, s47, v56
	v_mfma_f32_16x16x32_bf16 v[80:83], v[248:251], v[228:231], v[80:83]
	global_load_dwordx4 v[48:51], v[48:49], off offset:512
	s_nop 0
	v_mfma_f32_16x16x32_bf16 v[76:79], v[236:239], v[232:235], v[76:79]
	v_addc_co_u32_e32 v57, vcc, 0, v57, vcc
	v_mfma_f32_16x16x32_bf16 v[72:75], v[240:243], v[232:235], v[72:75]
	v_add_co_u32_e32 v60, vcc, s47, v60
	global_load_dwordx4 v[52:55], v[52:53], off offset:512
	v_mfma_f32_16x16x32_bf16 v[68:71], v[244:247], v[232:235], v[68:71]
	s_nop 0
	v_addc_co_u32_e32 v61, vcc, 0, v61, vcc
	v_mfma_f32_16x16x32_bf16 v[64:67], v[248:251], v[232:235], v[64:67]
	global_load_dwordx4 v[56:59], v[56:57], off offset:512
	global_load_dwordx4 v[60:63], v[60:61], off offset:512
	s_cbranch_scc1 .Lxk_206
	s_waitcnt vmcnt(0) lgkmcnt(0)
	s_waitcnt vmcnt(15)
	v_mov_b32_e32 v1, v192
	s_lshl_b32 s4, s4, 7
	v_lshlrev_b32_e32 v0, 8, v1
	v_and_b32_e32 v2, 15, v1
	v_bfe_u32 v3, v1, 4, 2
	v_and_b32_e32 v0, 0xffffc000, v0
	s_waitcnt vmcnt(13)
	v_lshl_or_b32 v4, v2, 8, v0
	v_bitop3_b32 v5, v3, v1, 15 bitop3:0x78
	v_bitop3_b32 v6, v3, v2, 4 bitop3:0x36
	v_bitop3_b32 v7, v3, v2, 8 bitop3:0x36
	v_bitop3_b32 v2, v3, v2, 12 bitop3:0x36
	v_lshl_or_b32 v5, v5, 4, v4
	v_lshl_or_b32 v6, v6, 4, v4
	v_lshl_or_b32 v7, v7, 4, v4
	v_lshl_or_b32 v2, v2, 4, v4
	ds_write_b128 v5, v[124:127]
	ds_write_b128 v6, v[120:123]
	ds_write_b128 v7, v[116:119]
	ds_write_b128 v2, v[112:115]
	ds_write_b128 v5, v[108:111] offset:4096
	ds_write_b128 v6, v[104:107] offset:4096
	ds_write_b128 v7, v[100:103] offset:4096
	ds_write_b128 v2, v[96:99] offset:4096
	ds_write_b128 v5, v[92:95] offset:8192
	ds_write_b128 v6, v[88:91] offset:8192
	ds_write_b128 v7, v[84:87] offset:8192
	ds_write_b128 v2, v[80:83] offset:8192
	ds_write_b128 v5, v[76:79] offset:12288
	ds_write_b128 v6, v[72:75] offset:12288
	ds_write_b128 v7, v[68:71] offset:12288
	ds_write_b128 v2, v[64:67] offset:12288
	v_and_b32_e32 v2, 7, v1
	v_and_b32_e32 v3, 64, v1
	v_lshlrev_b32_e32 v4, 3, v2
	v_or3_b32 v6, v3, s4, v4
	v_bfe_u32 v3, v1, 3, 3
	v_lshlrev_b32_e32 v2, 1, v2
	v_xor_b32_e32 v4, v3, v2
	v_lshl_or_b32 v8, v3, 8, v0
	v_lshlrev_b32_e32 v4, 4, v4
	v_or_b32_e32 v5, v8, v4
	s_waitcnt vmcnt(12)
	ds_read_b128 v[12:15], v5
	v_bitop3_b32 v5, v2, v3, 1 bitop3:0x36
	v_lshlrev_b32_e32 v5, 4, v5
	v_lshl_add_u32 v10, s6, 7, v132
	v_or_b32_e32 v8, v8, v5
	s_waitcnt vmcnt(11)
	ds_read_b128 v[16:19], v8
	v_or_b32_e32 v8, v3, v10
	v_ashrrev_i32_e32 v9, 31, v8
	v_ashrrev_i32_e32 v7, 31, v6
	v_lshlrev_b64 v[8:9], 11, v[8:9]
	s_waitcnt vmcnt(10)
	v_lshl_add_u64 v[20:21], s[2:3], 0, v[8:9]
	v_lshlrev_b64 v[8:9], 1, v[6:7]
	v_lshl_add_u64 v[6:7], v[20:21], 0, v[8:9]
	global_load_dwordx4 v[20:23], v[6:7], off
	v_or_b32_e32 v1, 1, v2
	s_add_i32 s11, s11, s10
	s_cmp_ge_i32 s11, s13
	s_waitcnt vmcnt(0)
	v_lshlrev_b32_e32 v11, 16, v20
	s_waitcnt lgkmcnt(1)
	v_fmamk_f32 v11, v11, 0x3fb504f3, v12
	v_and_b32_e32 v12, 0xffff0000, v20
	v_fmamk_f32 v12, v12, 0x3fb504f3, v13
	v_add_f32_e32 v11, 0, v11
	v_add_f32_e32 v12, 0, v12
	s_nop 1
	v_cvt_pk_bf16_f32 v12, v11, v12
	v_lshlrev_b32_e32 v11, 16, v21
	v_and_b32_e32 v13, 0xffff0000, v21
	v_fmamk_f32 v11, v11, 0x3fb504f3, v14
	v_fmac_f32_e32 v15, 0x3fb504f3, v13
	v_add_f32_e32 v11, 0, v11
	v_add_f32_e32 v13, 0, v15
	s_nop 1
	v_cvt_pk_bf16_f32 v13, v11, v13
	v_lshlrev_b32_e32 v11, 16, v22
	v_and_b32_e32 v14, 0xffff0000, v22
	s_waitcnt lgkmcnt(0)
	v_fmamk_f32 v11, v11, 0x3fb504f3, v16
	v_fmamk_f32 v14, v14, 0x3fb504f3, v17
	v_add_f32_e32 v11, 0, v11
	v_add_f32_e32 v14, 0, v14
	v_and_b32_e32 v15, 0xffff0000, v23
	s_nop 1
	v_cvt_pk_bf16_f32 v14, v11, v14
	v_lshlrev_b32_e32 v11, 16, v23
	v_fmac_f32_e32 v19, 0x3fb504f3, v15
	v_fmamk_f32 v11, v11, 0x3fb504f3, v18
	v_add_f32_e32 v15, 0, v19
	v_add_f32_e32 v11, 0, v11
	s_nop 1
	v_cvt_pk_bf16_f32 v15, v11, v15
	global_store_dwordx4 v[6:7], v[12:15], off
	v_or_b32_e32 v6, 8, v3
	v_lshl_or_b32 v7, v6, 8, v0
	v_bitop3_b32 v11, v3, v2, 8 bitop3:0x36
	v_lshl_or_b32 v11, v11, 4, v7
	ds_read_b128 v[12:15], v11
	v_bitop3_b32 v11, v3, v1, 8 bitop3:0x36
	v_lshl_or_b32 v7, v11, 4, v7
	v_or_b32_e32 v6, v6, v10
	ds_read_b128 v[16:19], v7
	v_ashrrev_i32_e32 v7, 31, v6
	v_lshlrev_b64 v[6:7], 11, v[6:7]
	v_lshl_add_u64 v[6:7], s[2:3], 0, v[6:7]
	v_lshl_add_u64 v[6:7], v[6:7], 0, v[8:9]
	global_load_dwordx4 v[20:23], v[6:7], off
	s_waitcnt vmcnt(0)
	v_lshlrev_b32_e32 v11, 16, v20
	s_waitcnt lgkmcnt(1)
	v_fmamk_f32 v11, v11, 0x3fb504f3, v12
	v_and_b32_e32 v12, 0xffff0000, v20
	v_fmamk_f32 v12, v12, 0x3fb504f3, v13
	v_add_f32_e32 v11, 0, v11
	v_add_f32_e32 v12, 0, v12
	s_nop 1
	v_cvt_pk_bf16_f32 v12, v11, v12
	v_lshlrev_b32_e32 v11, 16, v21
	v_and_b32_e32 v13, 0xffff0000, v21
	v_fmamk_f32 v11, v11, 0x3fb504f3, v14
	v_fmac_f32_e32 v15, 0x3fb504f3, v13
	v_add_f32_e32 v11, 0, v11
	v_add_f32_e32 v13, 0, v15
	s_nop 1
	v_cvt_pk_bf16_f32 v13, v11, v13
	v_lshlrev_b32_e32 v11, 16, v22
	v_and_b32_e32 v14, 0xffff0000, v22
	s_waitcnt lgkmcnt(0)
	v_fmamk_f32 v11, v11, 0x3fb504f3, v16
	v_fmamk_f32 v14, v14, 0x3fb504f3, v17
	v_add_f32_e32 v11, 0, v11
	v_add_f32_e32 v14, 0, v14
	v_and_b32_e32 v15, 0xffff0000, v23
	s_nop 1
	v_cvt_pk_bf16_f32 v14, v11, v14
	v_lshlrev_b32_e32 v11, 16, v23
	v_fmac_f32_e32 v19, 0x3fb504f3, v15
	v_fmamk_f32 v11, v11, 0x3fb504f3, v18
	v_add_f32_e32 v15, 0, v19
	v_add_f32_e32 v11, 0, v11
	s_nop 1
	v_cvt_pk_bf16_f32 v15, v11, v15
	global_store_dwordx4 v[6:7], v[12:15], off
	v_or_b32_e32 v6, 16, v3
	v_lshl_or_b32 v7, v6, 8, v0
	v_or_b32_e32 v11, v7, v4
	v_or_b32_e32 v7, v7, v5
	v_or_b32_e32 v6, v6, v10
	ds_read_b128 v[12:15], v11
	ds_read_b128 v[16:19], v7
	v_ashrrev_i32_e32 v7, 31, v6
	v_lshlrev_b64 v[6:7], 11, v[6:7]
	v_lshl_add_u64 v[6:7], s[2:3], 0, v[6:7]
	v_lshl_add_u64 v[6:7], v[6:7], 0, v[8:9]
	global_load_dwordx4 v[20:23], v[6:7], off
	s_waitcnt vmcnt(0)
	v_lshlrev_b32_e32 v11, 16, v20
	s_waitcnt lgkmcnt(1)
	v_fmamk_f32 v11, v11, 0x3fb504f3, v12
	v_and_b32_e32 v12, 0xffff0000, v20
	v_fmamk_f32 v12, v12, 0x3fb504f3, v13
	v_add_f32_e32 v11, 0, v11
	v_add_f32_e32 v12, 0, v12
	s_nop 1
	v_cvt_pk_bf16_f32 v12, v11, v12
	v_lshlrev_b32_e32 v11, 16, v21
	v_and_b32_e32 v13, 0xffff0000, v21
	v_fmamk_f32 v11, v11, 0x3fb504f3, v14
	v_fmac_f32_e32 v15, 0x3fb504f3, v13
	v_add_f32_e32 v11, 0, v11
	v_add_f32_e32 v13, 0, v15
	s_nop 1
	v_cvt_pk_bf16_f32 v13, v11, v13
	v_lshlrev_b32_e32 v11, 16, v22
	v_and_b32_e32 v14, 0xffff0000, v22
	s_waitcnt lgkmcnt(0)
	v_fmamk_f32 v11, v11, 0x3fb504f3, v16
	v_fmamk_f32 v14, v14, 0x3fb504f3, v17
	v_add_f32_e32 v11, 0, v11
	v_add_f32_e32 v14, 0, v14
	v_and_b32_e32 v15, 0xffff0000, v23
	s_nop 1
	v_cvt_pk_bf16_f32 v14, v11, v14
	v_lshlrev_b32_e32 v11, 16, v23
	v_fmac_f32_e32 v19, 0x3fb504f3, v15
	v_fmamk_f32 v11, v11, 0x3fb504f3, v18
	v_add_f32_e32 v15, 0, v19
	v_add_f32_e32 v11, 0, v11
	s_nop 1
	v_cvt_pk_bf16_f32 v15, v11, v15
	global_store_dwordx4 v[6:7], v[12:15], off
	v_or_b32_e32 v6, 24, v3
	v_lshl_or_b32 v7, v6, 8, v0
	v_bitop3_b32 v11, v6, v2, 15 bitop3:0x6c
	v_lshl_or_b32 v11, v11, 4, v7
	ds_read_b128 v[12:15], v11
	v_bitop3_b32 v11, v6, v1, 15 bitop3:0x6c
	v_lshl_or_b32 v7, v11, 4, v7
	v_or_b32_e32 v6, v6, v10
	ds_read_b128 v[16:19], v7
	v_ashrrev_i32_e32 v7, 31, v6
	v_lshlrev_b64 v[6:7], 11, v[6:7]
	v_lshl_add_u64 v[6:7], s[2:3], 0, v[6:7]
	v_lshl_add_u64 v[6:7], v[6:7], 0, v[8:9]
	global_load_dwordx4 v[20:23], v[6:7], off
	s_waitcnt vmcnt(0)
	v_lshlrev_b32_e32 v11, 16, v20
	s_waitcnt lgkmcnt(1)
	v_fmamk_f32 v11, v11, 0x3fb504f3, v12
	v_and_b32_e32 v12, 0xffff0000, v20
	v_fmamk_f32 v12, v12, 0x3fb504f3, v13
	v_add_f32_e32 v11, 0, v11
	v_add_f32_e32 v12, 0, v12
	s_nop 1
	v_cvt_pk_bf16_f32 v12, v11, v12
	v_lshlrev_b32_e32 v11, 16, v21
	v_and_b32_e32 v13, 0xffff0000, v21
	v_fmamk_f32 v11, v11, 0x3fb504f3, v14
	v_fmac_f32_e32 v15, 0x3fb504f3, v13
	v_add_f32_e32 v11, 0, v11
	v_add_f32_e32 v13, 0, v15
	s_nop 1
	v_cvt_pk_bf16_f32 v13, v11, v13
	v_lshlrev_b32_e32 v11, 16, v22
	v_and_b32_e32 v14, 0xffff0000, v22
	s_waitcnt lgkmcnt(0)
	v_fmamk_f32 v11, v11, 0x3fb504f3, v16
	v_fmamk_f32 v14, v14, 0x3fb504f3, v17
	v_add_f32_e32 v11, 0, v11
	v_add_f32_e32 v14, 0, v14
	v_and_b32_e32 v15, 0xffff0000, v23
	s_nop 1
	v_cvt_pk_bf16_f32 v14, v11, v14
	v_lshlrev_b32_e32 v11, 16, v23
	v_fmac_f32_e32 v19, 0x3fb504f3, v15
	v_fmamk_f32 v11, v11, 0x3fb504f3, v18
	v_add_f32_e32 v15, 0, v19
	v_add_f32_e32 v11, 0, v11
	s_nop 1
	v_cvt_pk_bf16_f32 v15, v11, v15
	global_store_dwordx4 v[6:7], v[12:15], off
	v_or_b32_e32 v6, 32, v3
	v_lshl_or_b32 v7, v6, 8, v0
	v_or_b32_e32 v11, v7, v4
	v_or_b32_e32 v7, v7, v5
	v_or_b32_e32 v6, v6, v10
	ds_read_b128 v[12:15], v11
	ds_read_b128 v[16:19], v7
	v_ashrrev_i32_e32 v7, 31, v6
	v_lshlrev_b64 v[6:7], 11, v[6:7]
	v_lshl_add_u64 v[6:7], s[2:3], 0, v[6:7]
	v_lshl_add_u64 v[6:7], v[6:7], 0, v[8:9]
	global_load_dwordx4 v[20:23], v[6:7], off
	s_waitcnt vmcnt(0)
	v_lshlrev_b32_e32 v11, 16, v20
	s_waitcnt lgkmcnt(1)
	v_fmamk_f32 v11, v11, 0x3fb504f3, v12
	v_and_b32_e32 v12, 0xffff0000, v20
	v_fmamk_f32 v12, v12, 0x3fb504f3, v13
	v_add_f32_e32 v11, 0, v11
	v_add_f32_e32 v12, 0, v12
	s_nop 1
	v_cvt_pk_bf16_f32 v12, v11, v12
	v_lshlrev_b32_e32 v11, 16, v21
	v_and_b32_e32 v13, 0xffff0000, v21
	v_fmamk_f32 v11, v11, 0x3fb504f3, v14
	v_fmac_f32_e32 v15, 0x3fb504f3, v13
	v_add_f32_e32 v11, 0, v11
	v_add_f32_e32 v13, 0, v15
	s_nop 1
	v_cvt_pk_bf16_f32 v13, v11, v13
	v_lshlrev_b32_e32 v11, 16, v22
	v_and_b32_e32 v14, 0xffff0000, v22
	s_waitcnt lgkmcnt(0)
	v_fmamk_f32 v11, v11, 0x3fb504f3, v16
	v_fmamk_f32 v14, v14, 0x3fb504f3, v17
	v_add_f32_e32 v11, 0, v11
	v_add_f32_e32 v14, 0, v14
	v_and_b32_e32 v15, 0xffff0000, v23
	s_nop 1
	v_cvt_pk_bf16_f32 v14, v11, v14
	v_lshlrev_b32_e32 v11, 16, v23
	v_fmac_f32_e32 v19, 0x3fb504f3, v15
	v_fmamk_f32 v11, v11, 0x3fb504f3, v18
	v_add_f32_e32 v15, 0, v19
	v_add_f32_e32 v11, 0, v11
	s_nop 1
	v_cvt_pk_bf16_f32 v15, v11, v15
	global_store_dwordx4 v[6:7], v[12:15], off
	v_or_b32_e32 v6, 40, v3
	v_lshl_or_b32 v7, v6, 8, v0
	v_bitop3_b32 v11, v6, v2, 15 bitop3:0x6c
	v_lshl_or_b32 v11, v11, 4, v7
	ds_read_b128 v[12:15], v11
	v_bitop3_b32 v11, v6, v1, 15 bitop3:0x6c
	v_lshl_or_b32 v7, v11, 4, v7
	v_or_b32_e32 v6, v6, v10
	ds_read_b128 v[16:19], v7
	v_ashrrev_i32_e32 v7, 31, v6
	v_lshlrev_b64 v[6:7], 11, v[6:7]
	v_lshl_add_u64 v[6:7], s[2:3], 0, v[6:7]
	v_lshl_add_u64 v[6:7], v[6:7], 0, v[8:9]
	global_load_dwordx4 v[20:23], v[6:7], off
	s_waitcnt vmcnt(0)
	v_lshlrev_b32_e32 v11, 16, v20
	s_waitcnt lgkmcnt(1)
	v_fmamk_f32 v11, v11, 0x3fb504f3, v12
	v_and_b32_e32 v12, 0xffff0000, v20
	v_fmamk_f32 v12, v12, 0x3fb504f3, v13
	v_add_f32_e32 v11, 0, v11
	v_add_f32_e32 v12, 0, v12
	s_nop 1
	v_cvt_pk_bf16_f32 v12, v11, v12
	v_lshlrev_b32_e32 v11, 16, v21
	v_and_b32_e32 v13, 0xffff0000, v21
	v_fmamk_f32 v11, v11, 0x3fb504f3, v14
	v_fmac_f32_e32 v15, 0x3fb504f3, v13
	v_add_f32_e32 v11, 0, v11
	v_add_f32_e32 v13, 0, v15
	s_nop 1
	v_cvt_pk_bf16_f32 v13, v11, v13
	v_lshlrev_b32_e32 v11, 16, v22
	v_and_b32_e32 v14, 0xffff0000, v22
	s_waitcnt lgkmcnt(0)
	v_fmamk_f32 v11, v11, 0x3fb504f3, v16
	v_fmamk_f32 v14, v14, 0x3fb504f3, v17
	v_add_f32_e32 v11, 0, v11
	v_add_f32_e32 v14, 0, v14
	s_nop 1
	v_cvt_pk_bf16_f32 v14, v11, v14
	v_lshlrev_b32_e32 v11, 16, v23
	v_and_b32_e32 v15, 0xffff0000, v23
	v_fmamk_f32 v11, v11, 0x3fb504f3, v18
	v_fmac_f32_e32 v19, 0x3fb504f3, v15
	v_add_f32_e32 v11, 0, v11
	v_add_f32_e32 v15, 0, v19
	s_nop 1
	v_cvt_pk_bf16_f32 v15, v11, v15
	v_or_b32_e32 v11, 48, v3
	v_or_b32_e32 v16, v11, v10
	v_ashrrev_i32_e32 v17, 31, v16
	v_lshlrev_b64 v[16:17], 11, v[16:17]
	v_lshl_add_u64 v[16:17], s[2:3], 0, v[16:17]
	v_lshl_add_u64 v[20:21], v[16:17], 0, v[8:9]
	global_load_dwordx4 v[16:19], v[20:21], off
	s_nop 0
	global_store_dwordx4 v[6:7], v[12:15], off
	v_lshl_or_b32 v6, v11, 8, v0
	v_or_b32_e32 v4, v6, v4
	ds_read_b128 v[12:15], v4
	v_or_b32_e32 v4, v6, v5
	ds_read_b128 v[4:7], v4
	s_waitcnt vmcnt(1)
	v_lshlrev_b32_e32 v11, 16, v16
	s_waitcnt lgkmcnt(1)
	v_fmamk_f32 v11, v11, 0x3fb504f3, v12
	v_and_b32_e32 v12, 0xffff0000, v16
	v_fmamk_f32 v12, v12, 0x3fb504f3, v13
	v_add_f32_e32 v11, 0, v11
	v_add_f32_e32 v12, 0, v12
	s_nop 1
	v_cvt_pk_bf16_f32 v12, v11, v12
	v_lshlrev_b32_e32 v11, 16, v17
	v_and_b32_e32 v13, 0xffff0000, v17
	v_fmamk_f32 v11, v11, 0x3fb504f3, v14
	v_fmac_f32_e32 v15, 0x3fb504f3, v13
	v_add_f32_e32 v11, 0, v11
	v_add_f32_e32 v13, 0, v15
	s_nop 1
	v_cvt_pk_bf16_f32 v13, v11, v13
	v_lshlrev_b32_e32 v11, 16, v18
	s_waitcnt lgkmcnt(0)
	v_fmamk_f32 v4, v11, 0x3fb504f3, v4
	v_and_b32_e32 v11, 0xffff0000, v18
	v_fmamk_f32 v5, v11, 0x3fb504f3, v5
	v_or_b32_e32 v11, 56, v3
	v_or_b32_e32 v10, v11, v10
	v_add_f32_e32 v4, 0, v4
	v_add_f32_e32 v5, 0, v5
	v_lshl_or_b32 v0, v11, 8, v0
	v_bitop3_b32 v2, v11, v2, 15 bitop3:0x6c
	v_bitop3_b32 v1, v11, v1, 15 bitop3:0x6c
	v_ashrrev_i32_e32 v11, 31, v10
	s_nop 1
	v_cvt_pk_bf16_f32 v14, v4, v5
	v_lshlrev_b32_e32 v4, 16, v19
	v_and_b32_e32 v5, 0xffff0000, v19
	v_lshlrev_b64 v[10:11], 11, v[10:11]
	v_fmamk_f32 v4, v4, 0x3fb504f3, v6
	v_fmac_f32_e32 v7, 0x3fb504f3, v5
	v_lshl_add_u64 v[10:11], s[2:3], 0, v[10:11]
	v_add_f32_e32 v4, 0, v4
	v_add_f32_e32 v5, 0, v7
	s_nop 1
	v_cvt_pk_bf16_f32 v15, v4, v5
	global_store_dwordx4 v[20:21], v[12:15], off
	v_lshl_or_b32 v2, v2, 4, v0
	ds_read_b128 v[4:7], v2
	v_lshl_add_u64 v[12:13], v[10:11], 0, v[8:9]
	global_load_dwordx4 v[8:11], v[12:13], off
	v_lshl_or_b32 v0, v1, 4, v0
	ds_read_b128 v[0:3], v0
	s_waitcnt vmcnt(0)
	v_lshlrev_b32_e32 v14, 16, v8
	v_and_b32_e32 v8, 0xffff0000, v8
	s_waitcnt lgkmcnt(1)
	v_fmamk_f32 v4, v14, 0x3fb504f3, v4
	v_fmamk_f32 v5, v8, 0x3fb504f3, v5
	v_add_f32_e32 v4, 0, v4
	v_add_f32_e32 v5, 0, v5
	s_nop 1
	v_cvt_pk_bf16_f32 v4, v4, v5
	v_lshlrev_b32_e32 v5, 16, v9
	v_fmamk_f32 v5, v5, 0x3fb504f3, v6
	v_and_b32_e32 v6, 0xffff0000, v9
	v_fmac_f32_e32 v7, 0x3fb504f3, v6
	v_add_f32_e32 v5, 0, v5
	v_add_f32_e32 v6, 0, v7
	s_nop 1
	v_cvt_pk_bf16_f32 v5, v5, v6
	v_lshlrev_b32_e32 v6, 16, v10
	s_waitcnt lgkmcnt(0)
	v_fmamk_f32 v0, v6, 0x3fb504f3, v0
	v_and_b32_e32 v6, 0xffff0000, v10
	v_fmamk_f32 v1, v6, 0x3fb504f3, v1
	v_add_f32_e32 v0, 0, v0
	v_add_f32_e32 v1, 0, v1
	s_nop 1
	v_cvt_pk_bf16_f32 v6, v0, v1
	v_lshlrev_b32_e32 v0, 16, v11
	v_and_b32_e32 v1, 0xffff0000, v11
	v_fmamk_f32 v0, v0, 0x3fb504f3, v2
	v_fmac_f32_e32 v3, 0x3fb504f3, v1
	v_add_f32_e32 v0, 0, v0
	v_add_f32_e32 v1, 0, v3
	s_nop 1
	v_cvt_pk_bf16_f32 v7, v0, v1
	global_store_dwordx4 v[12:13], v[4:7], off
	s_cbranch_scc0 .LBB0_201

.LBB0_1468:
	s_or_b64 exec, exec, s[2:3]
	s_load_dwordx2 s[0:1], s[58:59], 0x20
	s_waitcnt vmcnt(6)
	v_mov_b32_e32 v4, v192
	s_add_i32 s10, s55, 128
	s_sub_i32 vcc_lo, s10, s62
	s_cmp_ge_u32 s10, s62
	s_cselect_b32 s10, vcc_lo, s10
	s_cmpk_gt_i32 s10, 0x27f
	s_cbranch_scc1 .LBB0_1473
	v_and_b32_e32 v6, 63, v4
	v_lshlrev_b32_e32 v2, 1, v4
	v_ashrrev_i32_e32 v7, 5, v4
	s_waitcnt vmcnt(5)
	v_ashrrev_i32_e32 v9, 6, v4
	s_waitcnt vmcnt(1)
	v_add_u32_e32 v25, 0x100, v4
	v_add_u32_e32 v27, 0x200, v4
	s_waitcnt vmcnt(0)
	v_add_u32_e32 v29, 0x300, v4
	v_add_u32_e32 v31, 0x400, v4
	v_add_u32_e32 v33, 0x500, v4
	v_add_u32_e32 v35, 0x600, v4
	v_add_u32_e32 v37, 0x700, v4
	v_add_u32_e32 v17, 0x800, v4
	v_add_u32_e32 v18, 0x900, v4
	v_add_u32_e32 v19, 0xa00, v4
	v_add_u32_e32 v20, 0xb00, v4
	v_add_u32_e32 v21, 0xc00, v4
	v_add_u32_e32 v22, 0xd00, v4
	v_add_u32_e32 v23, 0xe00, v4
	v_add_u32_e32 v4, 0xf00, v4
	v_and_b32_e32 v5, 62, v2
	s_movk_i32 s2, 0x104
	v_ashrrev_i32_e32 v10, 6, v25
	v_ashrrev_i32_e32 v11, 6, v27
	v_ashrrev_i32_e32 v12, 6, v29
	v_ashrrev_i32_e32 v13, 6, v31
	v_ashrrev_i32_e32 v14, 6, v33
	v_ashrrev_i32_e32 v15, 6, v35
	v_ashrrev_i32_e32 v16, 6, v37
	v_ashrrev_i32_e32 v17, 6, v17
	v_ashrrev_i32_e32 v18, 6, v18
	v_ashrrev_i32_e32 v19, 6, v19
	v_ashrrev_i32_e32 v20, 6, v20
	v_ashrrev_i32_e32 v21, 6, v21
	v_ashrrev_i32_e32 v22, 6, v22
	v_ashrrev_i32_e32 v23, 6, v23
	v_ashrrev_i32_e32 v24, 6, v4
	v_ashrrev_i32_e32 v25, 5, v25
	v_ashrrev_i32_e32 v27, 5, v27
	v_ashrrev_i32_e32 v29, 5, v29
	v_ashrrev_i32_e32 v31, 5, v31
	v_ashrrev_i32_e32 v33, 5, v33
	v_ashrrev_i32_e32 v35, 5, v35
	v_ashrrev_i32_e32 v37, 5, v37
	v_lshlrev_b32_e32 v176, 2, v6
	v_lshlrev_b32_e32 v2, 1, v5
	v_mov_b32_e32 v3, v177
	v_lshlrev_b32_e32 v8, 2, v7
	v_mul_lo_u32 v39, v9, s2
	v_mul_lo_u32 v40, v10, s2
	v_mul_lo_u32 v41, v11, s2
	v_mul_lo_u32 v42, v12, s2
	v_mul_lo_u32 v43, v13, s2
	v_mul_lo_u32 v44, v14, s2
	v_mul_lo_u32 v45, v15, s2
	v_mul_lo_u32 v46, v16, s2
	v_mul_lo_u32 v47, v17, s2
	v_mul_lo_u32 v48, v18, s2
	v_mul_lo_u32 v49, v19, s2
	v_mul_lo_u32 v50, v20, s2
	v_mul_lo_u32 v51, v21, s2
	v_mul_lo_u32 v52, v22, s2
	v_mul_lo_u32 v53, v23, s2
	v_mul_lo_u32 v4, v24, s2
	v_lshlrev_b32_e32 v26, 2, v25
	v_lshlrev_b32_e32 v28, 2, v27
	v_lshlrev_b32_e32 v30, 2, v29
	v_lshlrev_b32_e32 v32, 2, v31
	v_lshlrev_b32_e32 v34, 2, v33
	v_lshlrev_b32_e32 v36, 2, v35
	v_lshlrev_b32_e32 v38, 2, v37
	s_waitcnt lgkmcnt(0)
	v_lshl_add_u64 v[0:1], s[0:1], 0, v[176:177]
	v_lshl_add_u64 v[2:3], s[8:9], 0, v[2:3]
	v_mad_u32_u24 v8, v5, s2, v8
	v_mad_u32_u24 v26, v5, s2, v26
	v_mad_u32_u24 v28, v5, s2, v28
	v_mad_u32_u24 v30, v5, s2, v30
	v_mad_u32_u24 v32, v5, s2, v32
	v_mad_u32_u24 v34, v5, s2, v34
	v_mad_u32_u24 v36, v5, s2, v36
	v_mad_u32_u24 v38, v5, s2, v38
	v_add_u32_e32 v39, v176, v39
	v_add_u32_e32 v40, v176, v40
	v_add_u32_e32 v41, v176, v41
	v_add_u32_e32 v42, v176, v42
	v_add_u32_e32 v43, v176, v43
	v_add_u32_e32 v44, v176, v44
	v_add_u32_e32 v45, v176, v45
	v_add_u32_e32 v46, v176, v46
	v_add_u32_e32 v47, v176, v47
	v_add_u32_e32 v48, v176, v48
	v_add_u32_e32 v49, v176, v49
	v_add_u32_e32 v50, v176, v50
	v_add_u32_e32 v51, v176, v51
	v_add_u32_e32 v52, v176, v52
	v_add_u32_e32 v53, v176, v53
	v_add_u32_e32 v54, v176, v4
	s_branch .LBB0_1471

.LBB0_1473:
	v_mov_b32_e32 v4, v192
	s_add_i32 s10, s55, 256
	s_sub_i32 vcc_lo, s10, s62
	s_cmp_ge_u32 s10, s62
	s_cselect_b32 s10, vcc_lo, s10
	s_cmpk_gt_i32 s10, 0xdf
	s_cbranch_scc1 .LBB0_1478
	v_and_b32_e32 v6, 63, v4
	v_lshlrev_b32_e32 v2, 1, v4
	v_lshlrev_b32_e32 v176, 2, v6
	v_and_b32_e32 v5, 62, v2
	s_waitcnt lgkmcnt(0)
	v_lshl_add_u64 v[0:1], s[0:1], 0, v[176:177]
	s_mov_b64 s[2:3], 0x3800
	v_lshlrev_b32_e32 v2, 1, v5
	v_mov_b32_e32 v3, v177
	v_lshl_add_u64 v[0:1], v[0:1], 0, s[2:3]
	v_lshl_add_u64 v[2:3], s[8:9], 0, v[2:3]
	s_mov_b64 s[2:3], 0x900000
	v_ashrrev_i32_e32 v7, 5, v4
	s_waitcnt vmcnt(5)
	v_ashrrev_i32_e32 v9, 6, v4
	s_waitcnt vmcnt(1)
	v_add_u32_e32 v25, 0x100, v4
	v_add_u32_e32 v27, 0x200, v4
	s_waitcnt vmcnt(0)
	v_add_u32_e32 v29, 0x300, v4
	v_add_u32_e32 v31, 0x400, v4
	v_add_u32_e32 v33, 0x500, v4
	v_add_u32_e32 v35, 0x600, v4
	v_add_u32_e32 v37, 0x700, v4
	v_add_u32_e32 v17, 0x800, v4
	v_add_u32_e32 v18, 0x900, v4
	v_add_u32_e32 v19, 0xa00, v4
	v_add_u32_e32 v20, 0xb00, v4
	v_add_u32_e32 v21, 0xc00, v4
	v_add_u32_e32 v22, 0xd00, v4
	v_add_u32_e32 v23, 0xe00, v4
	v_add_u32_e32 v4, 0xf00, v4
	v_lshl_add_u64 v[2:3], v[2:3], 0, s[2:3]
	s_movk_i32 s2, 0x104
	v_ashrrev_i32_e32 v10, 6, v25
	v_ashrrev_i32_e32 v11, 6, v27
	v_ashrrev_i32_e32 v12, 6, v29
	v_ashrrev_i32_e32 v13, 6, v31
	v_ashrrev_i32_e32 v14, 6, v33
	v_ashrrev_i32_e32 v15, 6, v35
	v_ashrrev_i32_e32 v16, 6, v37
	v_ashrrev_i32_e32 v17, 6, v17
	v_ashrrev_i32_e32 v18, 6, v18
	v_ashrrev_i32_e32 v19, 6, v19
	v_ashrrev_i32_e32 v20, 6, v20
	v_ashrrev_i32_e32 v21, 6, v21
	v_ashrrev_i32_e32 v22, 6, v22
	v_ashrrev_i32_e32 v23, 6, v23
	v_ashrrev_i32_e32 v24, 6, v4
	v_ashrrev_i32_e32 v25, 5, v25
	v_ashrrev_i32_e32 v27, 5, v27
	v_ashrrev_i32_e32 v29, 5, v29
	v_ashrrev_i32_e32 v31, 5, v31
	v_ashrrev_i32_e32 v33, 5, v33
	v_ashrrev_i32_e32 v35, 5, v35
	v_ashrrev_i32_e32 v37, 5, v37
	v_lshlrev_b32_e32 v8, 2, v7
	v_mul_lo_u32 v39, v9, s2
	v_mul_lo_u32 v40, v10, s2
	v_mul_lo_u32 v41, v11, s2
	v_mul_lo_u32 v42, v12, s2
	v_mul_lo_u32 v43, v13, s2
	v_mul_lo_u32 v44, v14, s2
	v_mul_lo_u32 v45, v15, s2
	v_mul_lo_u32 v46, v16, s2
	v_mul_lo_u32 v47, v17, s2
	v_mul_lo_u32 v48, v18, s2
	v_mul_lo_u32 v49, v19, s2
	v_mul_lo_u32 v50, v20, s2
	v_mul_lo_u32 v51, v21, s2
	v_mul_lo_u32 v52, v22, s2
	v_mul_lo_u32 v53, v23, s2
	v_mul_lo_u32 v4, v24, s2
	v_lshlrev_b32_e32 v26, 2, v25
	v_lshlrev_b32_e32 v28, 2, v27
	v_lshlrev_b32_e32 v30, 2, v29
	v_lshlrev_b32_e32 v32, 2, v31
	v_lshlrev_b32_e32 v34, 2, v33
	v_lshlrev_b32_e32 v36, 2, v35
	v_lshlrev_b32_e32 v38, 2, v37
	v_mad_u32_u24 v8, v5, s2, v8
	v_mad_u32_u24 v26, v5, s2, v26
	v_mad_u32_u24 v28, v5, s2, v28
	v_mad_u32_u24 v30, v5, s2, v30
	v_mad_u32_u24 v32, v5, s2, v32
	v_mad_u32_u24 v34, v5, s2, v34
	v_mad_u32_u24 v36, v5, s2, v36
	v_mad_u32_u24 v38, v5, s2, v38
	v_add_u32_e32 v39, v176, v39
	v_add_u32_e32 v40, v176, v40
	v_add_u32_e32 v41, v176, v41
	v_add_u32_e32 v42, v176, v42
	v_add_u32_e32 v43, v176, v43
	v_add_u32_e32 v44, v176, v44
	v_add_u32_e32 v45, v176, v45
	v_add_u32_e32 v46, v176, v46
	v_add_u32_e32 v47, v176, v47
	v_add_u32_e32 v48, v176, v48
	v_add_u32_e32 v49, v176, v49
	v_add_u32_e32 v50, v176, v50
	v_add_u32_e32 v51, v176, v51
	v_add_u32_e32 v52, v176, v52
	v_add_u32_e32 v53, v176, v53
	v_add_u32_e32 v54, v176, v4
	s_branch .LBB0_1476

.LBB0_1483:
	s_waitcnt vmcnt(2)
	v_mov_b32_e32 v22, v192
	s_add_i32 s10, s55, 32
	s_sub_i32 vcc_lo, s10, s62
	s_cmp_ge_u32 s10, s62
	s_cselect_b32 s10, vcc_lo, s10
	s_cmpk_gt_i32 s10, 0x13f
	s_movk_i32 s11, 0x1000
	s_cbranch_scc1 .LBB0_1488
	s_load_dwordx2 s[2:3], s[58:59], 0x78
	v_lshlrev_b32_e32 v0, 1, v22
	v_and_b32_e32 v4, 63, v22
	v_and_b32_e32 v36, 62, v0
	v_lshlrev_b32_e32 v176, 2, v4
	v_lshlrev_b32_e32 v2, 1, v36
	v_mov_b32_e32 v3, v177
	s_waitcnt lgkmcnt(0)
	v_lshl_add_u64 v[0:1], s[2:3], 0, v[176:177]
	v_lshl_add_u64 v[2:3], s[8:9], 0, v[2:3]
	s_mov_b64 s[2:3], 0x12c0000
	v_ashrrev_i32_e32 v5, 5, v22
	v_ashrrev_i32_e32 v7, 6, v22
	v_add_u32_e32 v23, 0x100, v22
	s_waitcnt vmcnt(1)
	v_add_u32_e32 v25, 0x200, v22
	v_add_u32_e32 v27, 0x300, v22
	s_waitcnt vmcnt(0)
	v_add_u32_e32 v29, 0x400, v22
	v_add_u32_e32 v31, 0x500, v22
	v_add_u32_e32 v33, 0x600, v22
	v_add_u32_e32 v35, 0x700, v22
	v_add_u32_e32 v15, 0x800, v22
	v_add_u32_e32 v16, 0x900, v22
	v_add_u32_e32 v17, 0xa00, v22
	v_add_u32_e32 v18, 0xb00, v22
	v_add_u32_e32 v19, 0xc00, v22
	v_add_u32_e32 v20, 0xd00, v22
	v_add_u32_e32 v21, 0xe00, v22
	v_add_u32_e32 v22, 0xf00, v22
	v_lshl_add_u64 v[2:3], v[2:3], 0, s[2:3]
	s_movk_i32 s2, 0x104
	v_ashrrev_i32_e32 v8, 6, v23
	v_ashrrev_i32_e32 v9, 6, v25
	v_ashrrev_i32_e32 v10, 6, v27
	v_ashrrev_i32_e32 v11, 6, v29
	v_ashrrev_i32_e32 v12, 6, v31
	v_ashrrev_i32_e32 v13, 6, v33
	v_ashrrev_i32_e32 v14, 6, v35
	v_ashrrev_i32_e32 v15, 6, v15
	v_ashrrev_i32_e32 v16, 6, v16
	v_ashrrev_i32_e32 v17, 6, v17
	v_ashrrev_i32_e32 v18, 6, v18
	v_ashrrev_i32_e32 v19, 6, v19
	v_ashrrev_i32_e32 v20, 6, v20
	v_ashrrev_i32_e32 v21, 6, v21
	v_ashrrev_i32_e32 v22, 6, v22
	v_ashrrev_i32_e32 v23, 5, v23
	v_ashrrev_i32_e32 v25, 5, v25
	v_ashrrev_i32_e32 v27, 5, v27
	v_ashrrev_i32_e32 v29, 5, v29
	v_ashrrev_i32_e32 v31, 5, v31
	v_ashrrev_i32_e32 v33, 5, v33
	v_ashrrev_i32_e32 v35, 5, v35
	v_lshlrev_b32_e32 v6, 2, v5
	v_mul_lo_u32 v37, v7, s2
	v_mul_lo_u32 v38, v8, s2
	v_mul_lo_u32 v39, v9, s2
	v_mul_lo_u32 v40, v10, s2
	v_mul_lo_u32 v41, v11, s2
	v_mul_lo_u32 v42, v12, s2
	v_mul_lo_u32 v43, v13, s2
	v_mul_lo_u32 v44, v14, s2
	v_mul_lo_u32 v45, v15, s2
	v_mul_lo_u32 v46, v16, s2
	v_mul_lo_u32 v47, v17, s2
	v_mul_lo_u32 v48, v18, s2
	v_mul_lo_u32 v49, v19, s2
	v_mul_lo_u32 v50, v20, s2
	v_mul_lo_u32 v51, v21, s2
	v_mul_lo_u32 v52, v22, s2
	v_lshlrev_b32_e32 v24, 2, v23
	v_lshlrev_b32_e32 v26, 2, v25
	v_lshlrev_b32_e32 v28, 2, v27
	v_lshlrev_b32_e32 v30, 2, v29
	v_lshlrev_b32_e32 v32, 2, v31
	v_lshlrev_b32_e32 v34, 2, v33
	v_lshlrev_b32_e32 v53, 2, v35
	v_mad_u32_u24 v6, v36, s2, v6
	v_mad_u32_u24 v24, v36, s2, v24
	v_mad_u32_u24 v26, v36, s2, v26
	v_mad_u32_u24 v28, v36, s2, v28
	v_mad_u32_u24 v30, v36, s2, v30
	v_mad_u32_u24 v32, v36, s2, v32
	v_mad_u32_u24 v34, v36, s2, v34
	v_mad_u32_u24 v36, v36, s2, v53
	v_add_u32_e32 v37, v176, v37
	v_add_u32_e32 v38, v176, v38
	v_add_u32_e32 v39, v176, v39
	v_add_u32_e32 v40, v176, v40
	v_add_u32_e32 v41, v176, v41
	v_add_u32_e32 v42, v176, v42
	v_add_u32_e32 v43, v176, v43
	v_add_u32_e32 v44, v176, v44
	v_add_u32_e32 v45, v176, v45
	v_add_u32_e32 v46, v176, v46
	v_add_u32_e32 v47, v176, v47
	v_add_u32_e32 v48, v176, v48
	v_add_u32_e32 v49, v176, v49
	v_add_u32_e32 v50, v176, v50
	v_add_u32_e32 v51, v176, v51
	v_add_u32_e32 v52, v176, v52
	s_branch .LBB0_1486

.LBB0_1505:
	s_lshl_b32 s56, s16, 14
	v_mov_b32_e32 v4, v192
	s_lshl_b32 s17, s16, 3
	s_sub_i32 s17, s55, s17
	s_cmp_ge_u32 s62, 0x200
	s_cselect_b32 vcc_lo, 0xfffffee0, 0
	s_add_i32 s17, s17, vcc_lo
	s_cmp_gt_u32 s17, 3
	s_cbranch_scc1 .LBB0_1510
	s_lshl_b32 s4, s56, 1
	v_lshlrev_b32_e32 v2, 1, v4
	s_add_u32 s4, s12, s4
	v_and_b32_e32 v5, 62, v2
	s_addc_u32 s5, s13, 0
	s_lshl_b64 s[6:7], s[56:57], 2
	v_and_b32_e32 v6, 63, v4
	v_lshlrev_b32_e32 v2, 1, v5
	v_mov_b32_e32 v3, v177
	v_ashrrev_i32_e32 v7, 5, v4
	v_ashrrev_i32_e32 v9, 6, v4
	s_waitcnt vmcnt(1)
	v_add_u32_e32 v25, 0x100, v4
	v_add_u32_e32 v27, 0x200, v4
	s_waitcnt vmcnt(0)
	v_add_u32_e32 v29, 0x300, v4
	v_add_u32_e32 v31, 0x400, v4
	v_add_u32_e32 v33, 0x500, v4
	v_add_u32_e32 v35, 0x600, v4
	v_add_u32_e32 v37, 0x700, v4
	v_add_u32_e32 v17, 0x800, v4
	v_add_u32_e32 v18, 0x900, v4
	v_add_u32_e32 v19, 0xa00, v4
	v_add_u32_e32 v20, 0xb00, v4
	v_add_u32_e32 v21, 0xc00, v4
	v_add_u32_e32 v22, 0xd00, v4
	v_add_u32_e32 v23, 0xe00, v4
	v_add_u32_e32 v4, 0xf00, v4
	s_add_u32 s6, s2, s6
	v_lshl_add_u64 v[2:3], s[4:5], 0, v[2:3]
	s_movk_i32 s4, 0x104
	v_ashrrev_i32_e32 v10, 6, v25
	v_ashrrev_i32_e32 v11, 6, v27
	v_ashrrev_i32_e32 v12, 6, v29
	v_ashrrev_i32_e32 v13, 6, v31
	v_ashrrev_i32_e32 v14, 6, v33
	v_ashrrev_i32_e32 v15, 6, v35
	v_ashrrev_i32_e32 v16, 6, v37
	v_ashrrev_i32_e32 v17, 6, v17
	v_ashrrev_i32_e32 v18, 6, v18
	v_ashrrev_i32_e32 v19, 6, v19
	v_ashrrev_i32_e32 v20, 6, v20
	v_ashrrev_i32_e32 v21, 6, v21
	v_ashrrev_i32_e32 v22, 6, v22
	v_ashrrev_i32_e32 v23, 6, v23
	v_ashrrev_i32_e32 v24, 6, v4
	v_ashrrev_i32_e32 v25, 5, v25
	v_ashrrev_i32_e32 v27, 5, v27
	v_ashrrev_i32_e32 v29, 5, v29
	v_ashrrev_i32_e32 v31, 5, v31
	v_ashrrev_i32_e32 v33, 5, v33
	v_ashrrev_i32_e32 v35, 5, v35
	v_ashrrev_i32_e32 v37, 5, v37
	s_addc_u32 s7, s3, s7
	v_lshlrev_b32_e32 v176, 2, v6
	v_lshlrev_b32_e32 v8, 2, v7
	v_mul_lo_u32 v39, v9, s4
	v_mul_lo_u32 v40, v10, s4
	v_mul_lo_u32 v41, v11, s4
	v_mul_lo_u32 v42, v12, s4
	v_mul_lo_u32 v43, v13, s4
	v_mul_lo_u32 v44, v14, s4
	v_mul_lo_u32 v45, v15, s4
	v_mul_lo_u32 v46, v16, s4
	v_mul_lo_u32 v47, v17, s4
	v_mul_lo_u32 v48, v18, s4
	v_mul_lo_u32 v49, v19, s4
	v_mul_lo_u32 v50, v20, s4
	v_mul_lo_u32 v51, v21, s4
	v_mul_lo_u32 v52, v22, s4
	v_mul_lo_u32 v53, v23, s4
	v_mul_lo_u32 v4, v24, s4
	v_lshlrev_b32_e32 v26, 2, v25
	v_lshlrev_b32_e32 v28, 2, v27
	v_lshlrev_b32_e32 v30, 2, v29
	v_lshlrev_b32_e32 v32, 2, v31
	v_lshlrev_b32_e32 v34, 2, v33
	v_lshlrev_b32_e32 v36, 2, v35
	v_lshlrev_b32_e32 v38, 2, v37
	v_lshl_add_u64 v[0:1], s[6:7], 0, v[176:177]
	v_mad_u32_u24 v8, v5, s4, v8
	v_mad_u32_u24 v26, v5, s4, v26
	v_mad_u32_u24 v28, v5, s4, v28
	v_mad_u32_u24 v30, v5, s4, v30
	v_mad_u32_u24 v32, v5, s4, v32
	v_mad_u32_u24 v34, v5, s4, v34
	v_mad_u32_u24 v36, v5, s4, v36
	v_mad_u32_u24 v38, v5, s4, v38
	v_add_u32_e32 v39, v176, v39
	v_add_u32_e32 v40, v176, v40
	v_add_u32_e32 v41, v176, v41
	v_add_u32_e32 v42, v176, v42
	v_add_u32_e32 v43, v176, v43
	v_add_u32_e32 v44, v176, v44
	v_add_u32_e32 v45, v176, v45
	v_add_u32_e32 v46, v176, v46
	v_add_u32_e32 v47, v176, v47
	v_add_u32_e32 v48, v176, v48
	v_add_u32_e32 v49, v176, v49
	v_add_u32_e32 v50, v176, v50
	v_add_u32_e32 v51, v176, v51
	v_add_u32_e32 v52, v176, v52
	v_add_u32_e32 v53, v176, v53
	v_add_u32_e32 v54, v176, v4
	s_branch .LBB0_1508

.LBB0_1510:
	v_mov_b32_e32 v4, v192
	s_lshl_b32 s17, s16, 3
	s_sub_i32 s17, s55, s17
	s_cmp_ge_u32 s62, 0x200
	s_cselect_b32 vcc_lo, 0xfffffee0, 0
	s_add_i32 s17, s17, vcc_lo
	s_add_i32 s17, s17, -4
	s_cmp_gt_u32 s17, 3
	s_cbranch_scc1 .LBB0_1504
	s_load_dwordx2 s[4:5], s[58:59], 0x48
	s_lshl_b32 s6, s56, 1
	s_add_u32 s6, s14, s6
	s_addc_u32 s7, s15, 0
	s_lshl_b64 s[10:11], s[56:57], 2
	s_waitcnt lgkmcnt(0)
	s_add_u32 s4, s4, s10
	v_and_b32_e32 v6, 63, v4
	s_addc_u32 s5, s5, s11
	v_lshlrev_b32_e32 v176, 2, v6
	v_lshlrev_b32_e32 v2, 1, v4
	v_ashrrev_i32_e32 v7, 5, v4
	v_ashrrev_i32_e32 v9, 6, v4
	s_waitcnt vmcnt(1)
	v_add_u32_e32 v25, 0x100, v4
	v_add_u32_e32 v27, 0x200, v4
	s_waitcnt vmcnt(0)
	v_add_u32_e32 v29, 0x300, v4
	v_add_u32_e32 v31, 0x400, v4
	v_add_u32_e32 v33, 0x500, v4
	v_add_u32_e32 v35, 0x600, v4
	v_add_u32_e32 v37, 0x700, v4
	v_add_u32_e32 v17, 0x800, v4
	v_add_u32_e32 v18, 0x900, v4
	v_add_u32_e32 v19, 0xa00, v4
	v_add_u32_e32 v20, 0xb00, v4
	v_add_u32_e32 v21, 0xc00, v4
	v_add_u32_e32 v22, 0xd00, v4
	v_add_u32_e32 v23, 0xe00, v4
	v_add_u32_e32 v4, 0xf00, v4
	v_lshl_add_u64 v[0:1], s[4:5], 0, v[176:177]
	v_and_b32_e32 v5, 62, v2
	s_movk_i32 s4, 0x104
	v_ashrrev_i32_e32 v10, 6, v25
	v_ashrrev_i32_e32 v11, 6, v27
	v_ashrrev_i32_e32 v12, 6, v29
	v_ashrrev_i32_e32 v13, 6, v31
	v_ashrrev_i32_e32 v14, 6, v33
	v_ashrrev_i32_e32 v15, 6, v35
	v_ashrrev_i32_e32 v16, 6, v37
	v_ashrrev_i32_e32 v17, 6, v17
	v_ashrrev_i32_e32 v18, 6, v18
	v_ashrrev_i32_e32 v19, 6, v19
	v_ashrrev_i32_e32 v20, 6, v20
	v_ashrrev_i32_e32 v21, 6, v21
	v_ashrrev_i32_e32 v22, 6, v22
	v_ashrrev_i32_e32 v23, 6, v23
	v_ashrrev_i32_e32 v24, 6, v4
	v_ashrrev_i32_e32 v25, 5, v25
	v_ashrrev_i32_e32 v27, 5, v27
	v_ashrrev_i32_e32 v29, 5, v29
	v_ashrrev_i32_e32 v31, 5, v31
	v_ashrrev_i32_e32 v33, 5, v33
	v_ashrrev_i32_e32 v35, 5, v35
	v_ashrrev_i32_e32 v37, 5, v37
	v_lshlrev_b32_e32 v2, 1, v5
	v_mov_b32_e32 v3, v177
	v_lshlrev_b32_e32 v8, 2, v7
	v_mul_lo_u32 v39, v9, s4
	v_mul_lo_u32 v40, v10, s4
	v_mul_lo_u32 v41, v11, s4
	v_mul_lo_u32 v42, v12, s4
	v_mul_lo_u32 v43, v13, s4
	v_mul_lo_u32 v44, v14, s4
	v_mul_lo_u32 v45, v15, s4
	v_mul_lo_u32 v46, v16, s4
	v_mul_lo_u32 v47, v17, s4
	v_mul_lo_u32 v48, v18, s4
	v_mul_lo_u32 v49, v19, s4
	v_mul_lo_u32 v50, v20, s4
	v_mul_lo_u32 v51, v21, s4
	v_mul_lo_u32 v52, v22, s4
	v_mul_lo_u32 v53, v23, s4
	v_mul_lo_u32 v4, v24, s4
	v_lshlrev_b32_e32 v26, 2, v25
	v_lshlrev_b32_e32 v28, 2, v27
	v_lshlrev_b32_e32 v30, 2, v29
	v_lshlrev_b32_e32 v32, 2, v31
	v_lshlrev_b32_e32 v34, 2, v33
	v_lshlrev_b32_e32 v36, 2, v35
	v_lshlrev_b32_e32 v38, 2, v37
	v_lshl_add_u64 v[2:3], s[6:7], 0, v[2:3]
	v_mad_u32_u24 v8, v5, s4, v8
	v_mad_u32_u24 v26, v5, s4, v26
	v_mad_u32_u24 v28, v5, s4, v28
	v_mad_u32_u24 v30, v5, s4, v30
	v_mad_u32_u24 v32, v5, s4, v32
	v_mad_u32_u24 v34, v5, s4, v34
	v_mad_u32_u24 v36, v5, s4, v36
	v_mad_u32_u24 v38, v5, s4, v38
	v_add_u32_e32 v39, v176, v39
	v_add_u32_e32 v40, v176, v40
	v_add_u32_e32 v41, v176, v41
	v_add_u32_e32 v42, v176, v42
	v_add_u32_e32 v43, v176, v43
	v_add_u32_e32 v44, v176, v44
	v_add_u32_e32 v45, v176, v45
	v_add_u32_e32 v46, v176, v46
	v_add_u32_e32 v47, v176, v47
	v_add_u32_e32 v48, v176, v48
	v_add_u32_e32 v49, v176, v49
	v_add_u32_e32 v50, v176, v50
	v_add_u32_e32 v51, v176, v51
	v_add_u32_e32 v52, v176, v52
	v_add_u32_e32 v53, v176, v53
	v_add_u32_e32 v54, v176, v4
	s_branch .LBB0_1513
